# EpiQrope rope-table loads batched under lane mask (16 per half) with counted vmcnt
# baseline (speedup 1.0000x reference)
.LBB0_599:
	v_lshl_add_u32 v146, s24, 8, v154
	v_mul_hi_i32 v144, v146, s60
	v_lshrrev_b32_e32 v145, 31, v144
	v_lshrrev_b32_e32 v144, 5, v144
	v_add_u32_e32 v144, v144, v145
	v_mul_lo_u32 v144, v144, s53
	v_sub_u32_e32 v144, v146, v144
	v_cmp_lt_i32_e32 vcc, s63, v144
	v_add_u32_e32 v144, 0xffffff80, v144
	v_lshl_add_u32 v150, s26, 8, v152
	v_ashrrev_i32_e32 v144, 1, v144
	v_ashrrev_i32_e32 v145, 31, v144
	v_ashrrev_i32_e32 v151, 31, v150
	v_lshlrev_b64 v[148:149], 3, v[144:145]
	v_lshlrev_b64 v[144:145], 8, v[150:151]
	v_lshl_add_u64 v[144:145], s[12:13], 0, v[144:145]
	s_and_saveexec_b64 s[100:101], vcc
	s_cbranch_execz .Lrope_skip0
	v_lshl_add_u64 v[248:249], v[144:145], 0, v[148:149]
	global_load_dwordx4 v[184:187], v[248:249], off
	global_load_dwordx4 v[188:191], v[248:249], off offset:16
	s_mov_b32 s98, 0x1000
	s_mov_b32 s99, 0
	v_lshl_add_u64 v[252:253], v[248:249], 0, s[98:99]
	global_load_dwordx4 v[192:195], v[252:253], off
	global_load_dwordx4 v[196:199], v[252:253], off offset:16
	s_mov_b32 s98, 0x2000
	s_mov_b32 s99, 0
	v_lshl_add_u64 v[252:253], v[248:249], 0, s[98:99]
	global_load_dwordx4 v[200:203], v[252:253], off
	global_load_dwordx4 v[204:207], v[252:253], off offset:16
	s_mov_b32 s98, 0x3000
	s_mov_b32 s99, 0
	v_lshl_add_u64 v[252:253], v[248:249], 0, s[98:99]
	global_load_dwordx4 v[208:211], v[252:253], off
	global_load_dwordx4 v[212:215], v[252:253], off offset:16
	s_mov_b32 s98, 0x8000
	s_mov_b32 s99, 0
	v_lshl_add_u64 v[252:253], v[248:249], 0, s[98:99]
	global_load_dwordx4 v[216:219], v[252:253], off
	global_load_dwordx4 v[220:223], v[252:253], off offset:16
	s_mov_b32 s98, 0x9000
	s_mov_b32 s99, 0
	v_lshl_add_u64 v[252:253], v[248:249], 0, s[98:99]
	global_load_dwordx4 v[224:227], v[252:253], off
	global_load_dwordx4 v[228:231], v[252:253], off offset:16
	s_mov_b32 s98, 0xa000
	s_mov_b32 s99, 0
	v_lshl_add_u64 v[252:253], v[248:249], 0, s[98:99]
	global_load_dwordx4 v[232:235], v[252:253], off
	global_load_dwordx4 v[236:239], v[252:253], off offset:16
	s_mov_b32 s98, 0xb000
	s_mov_b32 s99, 0
	v_lshl_add_u64 v[252:253], v[248:249], 0, s[98:99]
	global_load_dwordx4 v[240:243], v[252:253], off
	global_load_dwordx4 v[244:247], v[252:253], off offset:16
.Lrope_skip0:
	s_or_b64 exec, exec, s[100:101]
	s_and_saveexec_b64 s[24:25], vcc
	s_cbranch_execz .LBB0_601
	v_lshl_add_u64 v[162:163], v[144:145], 0, v[148:149]
	s_nop 0
	s_waitcnt vmcnt(14)
	v_pk_mul_f32 v[168:169], v[124:125], v[184:185] op_sel:[1,1] op_sel_hi:[0,1]
	v_mul_f32_e32 v170, v127, v187
	v_mul_f32_e32 v172, v126, v187
	v_pk_mul_f32 v[176:177], v[120:121], v[188:189] op_sel:[1,1] op_sel_hi:[0,1]
	v_mul_f32_e32 v178, v123, v191
	v_mul_f32_e32 v180, v122, v191
	v_pk_mul_f32 v[166:167], v[124:125], v[184:185]
	v_pk_mul_f32 v[174:175], v[120:121], v[188:189]
	v_pk_fma_f32 v[124:125], v[124:125], v[184:185], v[168:169] op_sel_hi:[1,0,1]
	v_pk_fma_f32 v[158:159], v[126:127], v[186:187], v[170:171] op_sel_hi:[1,1,0] neg_lo:[0,0,1] neg_hi:[0,0,1]
	v_pk_fma_f32 v[160:161], v[126:127], v[186:187], v[172:173] op_sel:[1,0,0] op_sel_hi:[0,1,0]
	v_pk_fma_f32 v[120:121], v[120:121], v[188:189], v[176:177] op_sel_hi:[1,0,1]
	v_pk_fma_f32 v[162:163], v[122:123], v[190:191], v[178:179] op_sel_hi:[1,1,0] neg_lo:[0,0,1] neg_hi:[0,0,1]
	v_pk_fma_f32 v[164:165], v[122:123], v[190:191], v[180:181] op_sel:[1,0,0] op_sel_hi:[0,1,0]
	v_sub_f32_e32 v124, v166, v168
	v_sub_f32_e32 v120, v174, v176
	v_mov_b32_e32 v126, v158
	v_mov_b32_e32 v127, v160
	v_mov_b32_e32 v122, v162
	v_mov_b32_e32 v123, v164
.LBB0_601:
	s_or_b64 exec, exec, s[24:25]
	v_cvt_pk_bf16_f32 v124, v124, v125
	v_cvt_pk_bf16_f32 v125, v126, v127
	v_cvt_pk_bf16_f32 v126, v120, v121
	v_mov_b64_e32 v[120:121], s[10:11]
	v_ashrrev_i32_e32 v147, 31, v146
	v_mad_i64_i32 v[120:121], s[24:25], v150, s64, v[120:121]
	v_cvt_pk_bf16_f32 v127, v122, v123
	v_lshl_add_u64 v[122:123], v[146:147], 1, v[120:121]
	global_store_dwordx4 v[122:123], v[124:127], off
	s_nop 1
	v_or_b32_e32 v124, 16, v150
	v_ashrrev_i32_e32 v125, 31, v124
	v_lshlrev_b64 v[120:121], 8, v[124:125]
	v_lshl_add_u64 v[120:121], s[12:13], 0, v[120:121]
	s_and_saveexec_b64 s[24:25], vcc
	s_cbranch_execz .LBB0_603
	v_lshl_add_u64 v[126:127], v[120:121], 0, v[148:149]
	s_waitcnt vmcnt(13)
	v_pk_mul_f32 v[166:167], v[116:117], v[192:193] op_sel:[1,1] op_sel_hi:[0,1]
	v_mul_f32_e32 v168, v119, v195
	v_mul_f32_e32 v170, v118, v195
	v_pk_mul_f32 v[174:175], v[112:113], v[196:197] op_sel:[1,1] op_sel_hi:[0,1]
	v_mul_f32_e32 v176, v115, v199
	v_mul_f32_e32 v178, v114, v199
	v_pk_mul_f32 v[126:127], v[116:117], v[192:193]
	v_pk_mul_f32 v[172:173], v[112:113], v[196:197]
	v_pk_fma_f32 v[116:117], v[116:117], v[192:193], v[166:167] op_sel_hi:[1,0,1]
	v_pk_fma_f32 v[158:159], v[118:119], v[194:195], v[168:169] op_sel_hi:[1,1,0] neg_lo:[0,0,1] neg_hi:[0,0,1]
	v_pk_fma_f32 v[160:161], v[118:119], v[194:195], v[170:171] op_sel:[1,0,0] op_sel_hi:[0,1,0]
	v_pk_fma_f32 v[112:113], v[112:113], v[196:197], v[174:175] op_sel_hi:[1,0,1]
	v_pk_fma_f32 v[162:163], v[114:115], v[198:199], v[176:177] op_sel_hi:[1,1,0] neg_lo:[0,0,1] neg_hi:[0,0,1]
	v_pk_fma_f32 v[164:165], v[114:115], v[198:199], v[178:179] op_sel:[1,0,0] op_sel_hi:[0,1,0]
	v_sub_f32_e32 v116, v126, v166
	v_sub_f32_e32 v112, v172, v174
	v_mov_b32_e32 v118, v158
	v_mov_b32_e32 v119, v160
	v_mov_b32_e32 v114, v162
	v_mov_b32_e32 v115, v164
.LBB0_603:
	s_or_b64 exec, exec, s[24:25]
	v_cvt_pk_bf16_f32 v116, v116, v117
	v_cvt_pk_bf16_f32 v117, v118, v119
	v_cvt_pk_bf16_f32 v118, v112, v113
	v_mov_b64_e32 v[112:113], s[10:11]
	v_mad_i64_i32 v[112:113], s[24:25], v124, s64, v[112:113]
	v_cvt_pk_bf16_f32 v119, v114, v115
	v_lshl_add_u64 v[114:115], v[146:147], 1, v[112:113]
	global_store_dwordx4 v[114:115], v[116:119], off
	s_nop 1
	v_or_b32_e32 v116, 32, v150
	v_ashrrev_i32_e32 v117, 31, v116
	v_lshlrev_b64 v[112:113], 8, v[116:117]
	v_lshl_add_u64 v[112:113], s[12:13], 0, v[112:113]
	s_and_saveexec_b64 s[24:25], vcc
	s_cbranch_execz .LBB0_605
	v_lshl_add_u64 v[118:119], v[112:113], 0, v[148:149]
	s_waitcnt vmcnt(12)
	v_pk_mul_f32 v[162:163], v[108:109], v[200:201] op_sel:[1,1] op_sel_hi:[0,1]
	v_mul_f32_e32 v164, v111, v203
	v_mul_f32_e32 v166, v110, v203
	v_pk_mul_f32 v[170:171], v[104:105], v[204:205] op_sel:[1,1] op_sel_hi:[0,1]
	v_mul_f32_e32 v172, v107, v207
	v_mul_f32_e32 v174, v106, v207
	v_pk_mul_f32 v[118:119], v[108:109], v[200:201]
	v_pk_mul_f32 v[168:169], v[104:105], v[204:205]
	v_pk_fma_f32 v[108:109], v[108:109], v[200:201], v[162:163] op_sel_hi:[1,0,1]
	v_pk_fma_f32 v[124:125], v[110:111], v[202:203], v[164:165] op_sel_hi:[1,1,0] neg_lo:[0,0,1] neg_hi:[0,0,1]
	v_pk_fma_f32 v[126:127], v[110:111], v[202:203], v[166:167] op_sel:[1,0,0] op_sel_hi:[0,1,0]
	v_pk_fma_f32 v[104:105], v[104:105], v[204:205], v[170:171] op_sel_hi:[1,0,1]
	v_pk_fma_f32 v[158:159], v[106:107], v[206:207], v[172:173] op_sel_hi:[1,1,0] neg_lo:[0,0,1] neg_hi:[0,0,1]
	v_pk_fma_f32 v[160:161], v[106:107], v[206:207], v[174:175] op_sel:[1,0,0] op_sel_hi:[0,1,0]
	v_sub_f32_e32 v108, v118, v162
	v_sub_f32_e32 v104, v168, v170
	v_mov_b32_e32 v110, v124
	v_mov_b32_e32 v111, v126
	v_mov_b32_e32 v106, v158
	v_mov_b32_e32 v107, v160
.LBB0_605:
	s_or_b64 exec, exec, s[24:25]
	v_cvt_pk_bf16_f32 v108, v108, v109
	v_cvt_pk_bf16_f32 v109, v110, v111
	v_cvt_pk_bf16_f32 v110, v104, v105
	v_mov_b64_e32 v[104:105], s[10:11]
	v_mad_i64_i32 v[104:105], s[24:25], v116, s64, v[104:105]
	v_cvt_pk_bf16_f32 v111, v106, v107
	v_lshl_add_u64 v[106:107], v[146:147], 1, v[104:105]
	global_store_dwordx4 v[106:107], v[108:111], off
	s_nop 1
	v_or_b32_e32 v108, 48, v150
	v_ashrrev_i32_e32 v109, 31, v108
	v_lshlrev_b64 v[104:105], 8, v[108:109]
	v_lshl_add_u64 v[104:105], s[12:13], 0, v[104:105]
	s_and_saveexec_b64 s[24:25], vcc
	s_cbranch_execz .LBB0_607
	v_lshl_add_u64 v[110:111], v[104:105], 0, v[148:149]
	s_waitcnt vmcnt(11)
	v_pk_mul_f32 v[158:159], v[100:101], v[208:209] op_sel:[1,1] op_sel_hi:[0,1]
	v_mul_f32_e32 v160, v103, v211
	v_mul_f32_e32 v162, v102, v211
	v_pk_mul_f32 v[166:167], v[96:97], v[212:213] op_sel:[1,1] op_sel_hi:[0,1]
	v_mul_f32_e32 v168, v99, v215
	v_mul_f32_e32 v170, v98, v215
	v_pk_mul_f32 v[110:111], v[100:101], v[208:209]
	v_pk_mul_f32 v[164:165], v[96:97], v[212:213]
	v_pk_fma_f32 v[100:101], v[100:101], v[208:209], v[158:159] op_sel_hi:[1,0,1]
	v_pk_fma_f32 v[116:117], v[102:103], v[210:211], v[160:161] op_sel_hi:[1,1,0] neg_lo:[0,0,1] neg_hi:[0,0,1]
	v_pk_fma_f32 v[118:119], v[102:103], v[210:211], v[162:163] op_sel:[1,0,0] op_sel_hi:[0,1,0]
	v_pk_fma_f32 v[96:97], v[96:97], v[212:213], v[166:167] op_sel_hi:[1,0,1]
	v_pk_fma_f32 v[124:125], v[98:99], v[214:215], v[168:169] op_sel_hi:[1,1,0] neg_lo:[0,0,1] neg_hi:[0,0,1]
	v_pk_fma_f32 v[126:127], v[98:99], v[214:215], v[170:171] op_sel:[1,0,0] op_sel_hi:[0,1,0]
	v_sub_f32_e32 v100, v110, v158
	v_sub_f32_e32 v96, v164, v166
	v_mov_b32_e32 v102, v116
	v_mov_b32_e32 v103, v118
	v_mov_b32_e32 v98, v124
	v_mov_b32_e32 v99, v126
.LBB0_607:
	s_or_b64 exec, exec, s[24:25]
	v_cvt_pk_bf16_f32 v100, v100, v101
	v_cvt_pk_bf16_f32 v101, v102, v103
	v_cvt_pk_bf16_f32 v102, v96, v97
	v_mov_b64_e32 v[96:97], s[10:11]
	v_mad_i64_i32 v[96:97], s[24:25], v108, s64, v[96:97]
	v_cvt_pk_bf16_f32 v103, v98, v99
	v_lshl_add_u64 v[98:99], v[146:147], 1, v[96:97]
	global_store_dwordx4 v[98:99], v[100:103], off
	s_nop 1
	v_add_u32_e32 v100, 0x80, v150
	v_ashrrev_i32_e32 v101, 31, v100
	v_lshlrev_b64 v[96:97], 8, v[100:101]
	v_lshl_add_u64 v[96:97], s[12:13], 0, v[96:97]
	s_and_saveexec_b64 s[24:25], vcc
	s_cbranch_execz .LBB0_609
	v_lshl_add_u64 v[102:103], v[96:97], 0, v[148:149]
	s_waitcnt vmcnt(10)
	v_pk_mul_f32 v[124:125], v[92:93], v[216:217] op_sel:[1,1] op_sel_hi:[0,1]
	v_mul_f32_e32 v126, v95, v219
	v_mul_f32_e32 v158, v94, v219
	v_pk_mul_f32 v[162:163], v[88:89], v[220:221] op_sel:[1,1] op_sel_hi:[0,1]
	v_mul_f32_e32 v164, v91, v223
	v_mul_f32_e32 v166, v90, v223
	v_pk_mul_f32 v[102:103], v[92:93], v[216:217]
	v_pk_mul_f32 v[160:161], v[88:89], v[220:221]
	v_pk_fma_f32 v[92:93], v[92:93], v[216:217], v[124:125] op_sel_hi:[1,0,1]
	v_pk_fma_f32 v[108:109], v[94:95], v[218:219], v[126:127] op_sel_hi:[1,1,0] neg_lo:[0,0,1] neg_hi:[0,0,1]
	v_pk_fma_f32 v[110:111], v[94:95], v[218:219], v[158:159] op_sel:[1,0,0] op_sel_hi:[0,1,0]
	v_pk_fma_f32 v[88:89], v[88:89], v[220:221], v[162:163] op_sel_hi:[1,0,1]
	v_pk_fma_f32 v[116:117], v[90:91], v[222:223], v[164:165] op_sel_hi:[1,1,0] neg_lo:[0,0,1] neg_hi:[0,0,1]
	v_pk_fma_f32 v[118:119], v[90:91], v[222:223], v[166:167] op_sel:[1,0,0] op_sel_hi:[0,1,0]
	v_sub_f32_e32 v92, v102, v124
	v_sub_f32_e32 v88, v160, v162
	v_mov_b32_e32 v94, v108
	v_mov_b32_e32 v95, v110
	v_mov_b32_e32 v90, v116
	v_mov_b32_e32 v91, v118
.LBB0_609:
	s_or_b64 exec, exec, s[24:25]
	v_cvt_pk_bf16_f32 v92, v92, v93
	v_cvt_pk_bf16_f32 v93, v94, v95
	v_cvt_pk_bf16_f32 v94, v88, v89
	v_mov_b64_e32 v[88:89], s[10:11]
	v_mad_i64_i32 v[88:89], s[24:25], v100, s64, v[88:89]
	v_cvt_pk_bf16_f32 v95, v90, v91
	v_lshl_add_u64 v[90:91], v[146:147], 1, v[88:89]
	global_store_dwordx4 v[90:91], v[92:95], off
	s_nop 1
	v_add_u32_e32 v92, 0x90, v150
	v_ashrrev_i32_e32 v93, 31, v92
	v_lshlrev_b64 v[88:89], 8, v[92:93]
	v_lshl_add_u64 v[88:89], s[12:13], 0, v[88:89]
	s_and_saveexec_b64 s[24:25], vcc
	s_cbranch_execz .LBB0_611
	v_lshl_add_u64 v[94:95], v[88:89], 0, v[148:149]
	s_waitcnt vmcnt(9)
	v_pk_mul_f32 v[116:117], v[84:85], v[224:225] op_sel:[1,1] op_sel_hi:[0,1]
	v_mul_f32_e32 v118, v87, v227
	v_mul_f32_e32 v124, v86, v227
	v_pk_mul_f32 v[158:159], v[80:81], v[228:229] op_sel:[1,1] op_sel_hi:[0,1]
	v_mul_f32_e32 v160, v83, v231
	v_mul_f32_e32 v162, v82, v231
	v_pk_mul_f32 v[94:95], v[84:85], v[224:225]
	v_pk_mul_f32 v[126:127], v[80:81], v[228:229]
	v_pk_fma_f32 v[84:85], v[84:85], v[224:225], v[116:117] op_sel_hi:[1,0,1]
	v_pk_fma_f32 v[100:101], v[86:87], v[226:227], v[118:119] op_sel_hi:[1,1,0] neg_lo:[0,0,1] neg_hi:[0,0,1]
	v_pk_fma_f32 v[102:103], v[86:87], v[226:227], v[124:125] op_sel:[1,0,0] op_sel_hi:[0,1,0]
	v_pk_fma_f32 v[80:81], v[80:81], v[228:229], v[158:159] op_sel_hi:[1,0,1]
	v_pk_fma_f32 v[108:109], v[82:83], v[230:231], v[160:161] op_sel_hi:[1,1,0] neg_lo:[0,0,1] neg_hi:[0,0,1]
	v_pk_fma_f32 v[110:111], v[82:83], v[230:231], v[162:163] op_sel:[1,0,0] op_sel_hi:[0,1,0]
	v_sub_f32_e32 v84, v94, v116
	v_sub_f32_e32 v80, v126, v158
	v_mov_b32_e32 v86, v100
	v_mov_b32_e32 v87, v102
	v_mov_b32_e32 v82, v108
	v_mov_b32_e32 v83, v110
.LBB0_611:
	s_or_b64 exec, exec, s[24:25]
	v_cvt_pk_bf16_f32 v84, v84, v85
	v_cvt_pk_bf16_f32 v85, v86, v87
	v_cvt_pk_bf16_f32 v86, v80, v81
	v_mov_b64_e32 v[80:81], s[10:11]
	v_mad_i64_i32 v[80:81], s[24:25], v92, s64, v[80:81]
	v_cvt_pk_bf16_f32 v87, v82, v83
	v_lshl_add_u64 v[82:83], v[146:147], 1, v[80:81]
	global_store_dwordx4 v[82:83], v[84:87], off
	s_nop 1
	v_add_u32_e32 v84, 0xa0, v150
	v_ashrrev_i32_e32 v85, 31, v84
	v_lshlrev_b64 v[80:81], 8, v[84:85]
	v_lshl_add_u64 v[80:81], s[12:13], 0, v[80:81]
	s_and_saveexec_b64 s[24:25], vcc
	s_cbranch_execz .LBB0_613
	v_lshl_add_u64 v[86:87], v[80:81], 0, v[148:149]
	s_waitcnt vmcnt(8)
	v_pk_mul_f32 v[108:109], v[76:77], v[232:233] op_sel:[1,1] op_sel_hi:[0,1]
	v_mul_f32_e32 v110, v79, v235
	v_mul_f32_e32 v116, v78, v235
	v_pk_mul_f32 v[124:125], v[72:73], v[236:237] op_sel:[1,1] op_sel_hi:[0,1]
	v_mul_f32_e32 v126, v75, v239
	v_mul_f32_e32 v158, v74, v239
	v_pk_mul_f32 v[86:87], v[76:77], v[232:233]
	v_pk_mul_f32 v[118:119], v[72:73], v[236:237]
	v_pk_fma_f32 v[76:77], v[76:77], v[232:233], v[108:109] op_sel_hi:[1,0,1]
	v_pk_fma_f32 v[92:93], v[78:79], v[234:235], v[110:111] op_sel_hi:[1,1,0] neg_lo:[0,0,1] neg_hi:[0,0,1]
	v_pk_fma_f32 v[94:95], v[78:79], v[234:235], v[116:117] op_sel:[1,0,0] op_sel_hi:[0,1,0]
	v_pk_fma_f32 v[72:73], v[72:73], v[236:237], v[124:125] op_sel_hi:[1,0,1]
	v_pk_fma_f32 v[100:101], v[74:75], v[238:239], v[126:127] op_sel_hi:[1,1,0] neg_lo:[0,0,1] neg_hi:[0,0,1]
	v_pk_fma_f32 v[102:103], v[74:75], v[238:239], v[158:159] op_sel:[1,0,0] op_sel_hi:[0,1,0]
	v_sub_f32_e32 v76, v86, v108
	v_sub_f32_e32 v72, v118, v124
	v_mov_b32_e32 v78, v92
	v_mov_b32_e32 v79, v94
	v_mov_b32_e32 v74, v100
	v_mov_b32_e32 v75, v102
.LBB0_613:
	s_or_b64 exec, exec, s[24:25]
	v_cvt_pk_bf16_f32 v76, v76, v77
	v_cvt_pk_bf16_f32 v77, v78, v79
	v_cvt_pk_bf16_f32 v78, v72, v73
	v_mov_b64_e32 v[72:73], s[10:11]
	v_mad_i64_i32 v[72:73], s[24:25], v84, s64, v[72:73]
	v_cvt_pk_bf16_f32 v79, v74, v75
	v_lshl_add_u64 v[74:75], v[146:147], 1, v[72:73]
	global_store_dwordx4 v[74:75], v[76:79], off
	s_nop 1
	v_add_u32_e32 v76, 0xb0, v150
	v_ashrrev_i32_e32 v77, 31, v76
	v_lshlrev_b64 v[72:73], 8, v[76:77]
	v_lshl_add_u64 v[72:73], s[12:13], 0, v[72:73]
	s_and_saveexec_b64 s[24:25], vcc
	s_cbranch_execz .LBB0_615
	v_lshl_add_u64 v[78:79], v[72:73], 0, v[148:149]
	s_waitcnt vmcnt(7)
	v_pk_mul_f32 v[100:101], v[68:69], v[240:241] op_sel:[1,1] op_sel_hi:[0,1]
	v_mul_f32_e32 v102, v71, v243
	v_mul_f32_e32 v108, v70, v243
	v_pk_mul_f32 v[116:117], v[64:65], v[244:245] op_sel:[1,1] op_sel_hi:[0,1]
	v_mul_f32_e32 v118, v67, v247
	v_mul_f32_e32 v124, v66, v247
	v_pk_mul_f32 v[78:79], v[68:69], v[240:241]
	v_pk_mul_f32 v[110:111], v[64:65], v[244:245]
	v_pk_fma_f32 v[68:69], v[68:69], v[240:241], v[100:101] op_sel_hi:[1,0,1]
	v_pk_fma_f32 v[84:85], v[70:71], v[242:243], v[102:103] op_sel_hi:[1,1,0] neg_lo:[0,0,1] neg_hi:[0,0,1]
	v_pk_fma_f32 v[86:87], v[70:71], v[242:243], v[108:109] op_sel:[1,0,0] op_sel_hi:[0,1,0]
	v_pk_fma_f32 v[64:65], v[64:65], v[244:245], v[116:117] op_sel_hi:[1,0,1]
	v_pk_fma_f32 v[92:93], v[66:67], v[246:247], v[118:119] op_sel_hi:[1,1,0] neg_lo:[0,0,1] neg_hi:[0,0,1]
	v_pk_fma_f32 v[94:95], v[66:67], v[246:247], v[124:125] op_sel:[1,0,0] op_sel_hi:[0,1,0]
	v_sub_f32_e32 v68, v78, v100
	v_sub_f32_e32 v64, v110, v116
	v_mov_b32_e32 v70, v84
	v_mov_b32_e32 v71, v86
	v_mov_b32_e32 v66, v92
	v_mov_b32_e32 v67, v94
.LBB0_615:
	s_or_b64 exec, exec, s[24:25]
	v_cvt_pk_bf16_f32 v68, v68, v69
	v_cvt_pk_bf16_f32 v69, v70, v71
	v_cvt_pk_bf16_f32 v70, v64, v65
	v_mov_b64_e32 v[64:65], s[10:11]
	v_cvt_pk_bf16_f32 v71, v66, v67
	v_mad_i64_i32 v[64:65], s[24:25], v76, s64, v[64:65]
	v_add_u32_e32 v66, 0x80, v146
	v_lshl_add_u64 v[64:65], v[146:147], 1, v[64:65]
	v_mul_hi_i32 v67, v66, s60
	global_store_dwordx4 v[64:65], v[68:71], off
	s_nop 1
	v_lshrrev_b32_e32 v68, 31, v67
	v_lshrrev_b32_e32 v67, 5, v67
	v_add_u32_e32 v67, v67, v68
	v_mul_lo_u32 v67, v67, s53
	v_sub_u32_e32 v66, v66, v67
	v_cmp_lt_i32_e32 vcc, s63, v66
	v_add_u32_e32 v66, 0xffffff80, v66
	v_ashrrev_i32_e32 v66, 1, v66
	v_ashrrev_i32_e32 v67, 31, v66
	v_lshlrev_b64 v[66:67], 3, v[66:67]
	s_and_saveexec_b64 s[100:101], vcc
	s_cbranch_execz .Lrope_skip1
	v_lshl_add_u64 v[248:249], v[144:145], 0, v[66:67]
	global_load_dwordx4 v[184:187], v[248:249], off
	global_load_dwordx4 v[188:191], v[248:249], off offset:16
	s_mov_b32 s98, 0x1000
	s_mov_b32 s99, 0
	v_lshl_add_u64 v[252:253], v[248:249], 0, s[98:99]
	global_load_dwordx4 v[192:195], v[252:253], off
	global_load_dwordx4 v[196:199], v[252:253], off offset:16
	s_mov_b32 s98, 0x2000
	s_mov_b32 s99, 0
	v_lshl_add_u64 v[252:253], v[248:249], 0, s[98:99]
	global_load_dwordx4 v[200:203], v[252:253], off
	global_load_dwordx4 v[204:207], v[252:253], off offset:16
	s_mov_b32 s98, 0x3000
	s_mov_b32 s99, 0
	v_lshl_add_u64 v[252:253], v[248:249], 0, s[98:99]
	global_load_dwordx4 v[208:211], v[252:253], off
	global_load_dwordx4 v[212:215], v[252:253], off offset:16
	s_mov_b32 s98, 0x8000
	s_mov_b32 s99, 0
	v_lshl_add_u64 v[252:253], v[248:249], 0, s[98:99]
	global_load_dwordx4 v[216:219], v[252:253], off
	global_load_dwordx4 v[220:223], v[252:253], off offset:16
	s_mov_b32 s98, 0x9000
	s_mov_b32 s99, 0
	v_lshl_add_u64 v[252:253], v[248:249], 0, s[98:99]
	global_load_dwordx4 v[224:227], v[252:253], off
	global_load_dwordx4 v[228:231], v[252:253], off offset:16
	s_mov_b32 s98, 0xa000
	s_mov_b32 s99, 0
	v_lshl_add_u64 v[252:253], v[248:249], 0, s[98:99]
	global_load_dwordx4 v[232:235], v[252:253], off
	global_load_dwordx4 v[236:239], v[252:253], off offset:16
	s_mov_b32 s98, 0xb000
	s_mov_b32 s99, 0
	v_lshl_add_u64 v[252:253], v[248:249], 0, s[98:99]
	global_load_dwordx4 v[240:243], v[252:253], off
	global_load_dwordx4 v[244:247], v[252:253], off offset:16
.Lrope_skip1:
	s_or_b64 exec, exec, s[100:101]
	s_and_saveexec_b64 s[24:25], vcc
	s_cbranch_execz .LBB0_617
	v_lshl_add_u64 v[76:77], v[144:145], 0, v[66:67]
	s_nop 0
	s_waitcnt vmcnt(14)
	v_pk_mul_f32 v[86:87], v[60:61], v[184:185] op_sel:[1,1] op_sel_hi:[0,1]
	v_mul_f32_e32 v92, v63, v187
	v_mul_f32_e32 v94, v62, v187
	v_pk_mul_f32 v[102:103], v[56:57], v[188:189] op_sel:[1,1] op_sel_hi:[0,1]
	v_mul_f32_e32 v108, v59, v191
	v_mul_f32_e32 v110, v58, v191
	v_pk_mul_f32 v[84:85], v[60:61], v[184:185]
	v_pk_mul_f32 v[100:101], v[56:57], v[188:189]
	v_pk_fma_f32 v[60:61], v[60:61], v[184:185], v[86:87] op_sel_hi:[1,0,1]
	v_pk_fma_f32 v[68:69], v[62:63], v[186:187], v[92:93] op_sel_hi:[1,1,0] neg_lo:[0,0,1] neg_hi:[0,0,1]
	v_pk_fma_f32 v[70:71], v[62:63], v[186:187], v[94:95] op_sel:[1,0,0] op_sel_hi:[0,1,0]
	v_pk_fma_f32 v[56:57], v[56:57], v[188:189], v[102:103] op_sel_hi:[1,0,1]
	v_pk_fma_f32 v[76:77], v[58:59], v[190:191], v[108:109] op_sel_hi:[1,1,0] neg_lo:[0,0,1] neg_hi:[0,0,1]
	v_pk_fma_f32 v[78:79], v[58:59], v[190:191], v[110:111] op_sel:[1,0,0] op_sel_hi:[0,1,0]
	v_sub_f32_e32 v60, v84, v86
	v_sub_f32_e32 v56, v100, v102
	v_mov_b32_e32 v62, v68
	v_mov_b32_e32 v63, v70
	v_mov_b32_e32 v58, v76
	v_mov_b32_e32 v59, v78
.LBB0_617:
	s_or_b64 exec, exec, s[24:25]
	v_cvt_pk_bf16_f32 v60, v60, v61
	v_cvt_pk_bf16_f32 v61, v62, v63
	v_cvt_pk_bf16_f32 v62, v56, v57
	v_cvt_pk_bf16_f32 v63, v58, v59
	global_store_dwordx4 v[122:123], v[60:63], off offset:256
	s_and_saveexec_b64 s[24:25], vcc
	s_cbranch_execz .LBB0_619
	v_lshl_add_u64 v[60:61], v[120:121], 0, v[66:67]
	s_nop 0
	s_waitcnt vmcnt(13)
	v_pk_mul_f32 v[70:71], v[52:53], v[192:193] op_sel:[1,1] op_sel_hi:[0,1]
	v_mul_f32_e32 v76, v55, v195
	v_mul_f32_e32 v78, v54, v195
	v_pk_mul_f32 v[86:87], v[48:49], v[196:197] op_sel:[1,1] op_sel_hi:[0,1]
	v_mul_f32_e32 v92, v51, v199
	v_mul_f32_e32 v94, v50, v199
	v_pk_mul_f32 v[68:69], v[52:53], v[192:193]
	v_pk_mul_f32 v[84:85], v[48:49], v[196:197]
	v_pk_fma_f32 v[52:53], v[52:53], v[192:193], v[70:71] op_sel_hi:[1,0,1]
	v_pk_fma_f32 v[56:57], v[54:55], v[194:195], v[76:77] op_sel_hi:[1,1,0] neg_lo:[0,0,1] neg_hi:[0,0,1]
	v_pk_fma_f32 v[58:59], v[54:55], v[194:195], v[78:79] op_sel:[1,0,0] op_sel_hi:[0,1,0]
	v_pk_fma_f32 v[48:49], v[48:49], v[196:197], v[86:87] op_sel_hi:[1,0,1]
	v_pk_fma_f32 v[60:61], v[50:51], v[198:199], v[92:93] op_sel_hi:[1,1,0] neg_lo:[0,0,1] neg_hi:[0,0,1]
	v_pk_fma_f32 v[62:63], v[50:51], v[198:199], v[94:95] op_sel:[1,0,0] op_sel_hi:[0,1,0]
	v_sub_f32_e32 v52, v68, v70
	v_sub_f32_e32 v48, v84, v86
	v_mov_b32_e32 v54, v56
	v_mov_b32_e32 v55, v58
	v_mov_b32_e32 v50, v60
	v_mov_b32_e32 v51, v62
.LBB0_619:
	s_or_b64 exec, exec, s[24:25]
	v_cvt_pk_bf16_f32 v52, v52, v53
	v_cvt_pk_bf16_f32 v53, v54, v55
	v_cvt_pk_bf16_f32 v54, v48, v49
	v_cvt_pk_bf16_f32 v55, v50, v51
	global_store_dwordx4 v[114:115], v[52:55], off offset:256
	s_and_saveexec_b64 s[24:25], vcc
	s_cbranch_execz .LBB0_621
	v_lshl_add_u64 v[52:53], v[112:113], 0, v[66:67]
	s_nop 0
	s_waitcnt vmcnt(12)
	v_pk_mul_f32 v[58:59], v[44:45], v[200:201] op_sel:[1,1] op_sel_hi:[0,1]
	v_mul_f32_e32 v60, v47, v203
	v_mul_f32_e32 v62, v46, v203
	v_pk_mul_f32 v[70:71], v[40:41], v[204:205] op_sel:[1,1] op_sel_hi:[0,1]
	v_mul_f32_e32 v76, v43, v207
	v_mul_f32_e32 v78, v42, v207
	v_pk_mul_f32 v[56:57], v[44:45], v[200:201]
	v_pk_mul_f32 v[68:69], v[40:41], v[204:205]
	v_pk_fma_f32 v[44:45], v[44:45], v[200:201], v[58:59] op_sel_hi:[1,0,1]
	v_pk_fma_f32 v[48:49], v[46:47], v[202:203], v[60:61] op_sel_hi:[1,1,0] neg_lo:[0,0,1] neg_hi:[0,0,1]
	v_pk_fma_f32 v[50:51], v[46:47], v[202:203], v[62:63] op_sel:[1,0,0] op_sel_hi:[0,1,0]
	v_pk_fma_f32 v[40:41], v[40:41], v[204:205], v[70:71] op_sel_hi:[1,0,1]
	v_pk_fma_f32 v[52:53], v[42:43], v[206:207], v[76:77] op_sel_hi:[1,1,0] neg_lo:[0,0,1] neg_hi:[0,0,1]
	v_pk_fma_f32 v[54:55], v[42:43], v[206:207], v[78:79] op_sel:[1,0,0] op_sel_hi:[0,1,0]
	v_sub_f32_e32 v44, v56, v58
	v_sub_f32_e32 v40, v68, v70
	v_mov_b32_e32 v46, v48
	v_mov_b32_e32 v47, v50
	v_mov_b32_e32 v42, v52
	v_mov_b32_e32 v43, v54
.LBB0_621:
	s_or_b64 exec, exec, s[24:25]
	v_cvt_pk_bf16_f32 v44, v44, v45
	v_cvt_pk_bf16_f32 v45, v46, v47
	v_cvt_pk_bf16_f32 v46, v40, v41
	v_cvt_pk_bf16_f32 v47, v42, v43
	global_store_dwordx4 v[106:107], v[44:47], off offset:256
	s_and_saveexec_b64 s[24:25], vcc
	s_cbranch_execz .LBB0_623
	v_lshl_add_u64 v[44:45], v[104:105], 0, v[66:67]
	s_nop 0
	s_waitcnt vmcnt(11)
	v_pk_mul_f32 v[50:51], v[36:37], v[208:209] op_sel:[1,1] op_sel_hi:[0,1]
	v_mul_f32_e32 v52, v39, v211
	v_mul_f32_e32 v54, v38, v211
	v_pk_mul_f32 v[58:59], v[32:33], v[212:213] op_sel:[1,1] op_sel_hi:[0,1]
	v_mul_f32_e32 v60, v35, v215
	v_mul_f32_e32 v62, v34, v215
	v_pk_mul_f32 v[48:49], v[36:37], v[208:209]
	v_pk_mul_f32 v[56:57], v[32:33], v[212:213]
	v_pk_fma_f32 v[36:37], v[36:37], v[208:209], v[50:51] op_sel_hi:[1,0,1]
	v_pk_fma_f32 v[40:41], v[38:39], v[210:211], v[52:53] op_sel_hi:[1,1,0] neg_lo:[0,0,1] neg_hi:[0,0,1]
	v_pk_fma_f32 v[42:43], v[38:39], v[210:211], v[54:55] op_sel:[1,0,0] op_sel_hi:[0,1,0]
	v_pk_fma_f32 v[32:33], v[32:33], v[212:213], v[58:59] op_sel_hi:[1,0,1]
	v_pk_fma_f32 v[44:45], v[34:35], v[214:215], v[60:61] op_sel_hi:[1,1,0] neg_lo:[0,0,1] neg_hi:[0,0,1]
	v_pk_fma_f32 v[46:47], v[34:35], v[214:215], v[62:63] op_sel:[1,0,0] op_sel_hi:[0,1,0]
	v_sub_f32_e32 v36, v48, v50
	v_sub_f32_e32 v32, v56, v58
	v_mov_b32_e32 v38, v40
	v_mov_b32_e32 v39, v42
	v_mov_b32_e32 v34, v44
	v_mov_b32_e32 v35, v46
.LBB0_623:
	s_or_b64 exec, exec, s[24:25]
	v_cvt_pk_bf16_f32 v36, v36, v37
	v_cvt_pk_bf16_f32 v37, v38, v39
	v_cvt_pk_bf16_f32 v38, v32, v33
	v_cvt_pk_bf16_f32 v39, v34, v35
	global_store_dwordx4 v[98:99], v[36:39], off offset:256
	s_and_saveexec_b64 s[24:25], vcc
	s_cbranch_execz .LBB0_625
	v_lshl_add_u64 v[36:37], v[96:97], 0, v[66:67]
	s_nop 0
	s_waitcnt vmcnt(10)
	v_pk_mul_f32 v[42:43], v[28:29], v[216:217] op_sel:[1,1] op_sel_hi:[0,1]
	v_mul_f32_e32 v44, v31, v219
	v_mul_f32_e32 v46, v30, v219
	v_pk_mul_f32 v[50:51], v[24:25], v[220:221] op_sel:[1,1] op_sel_hi:[0,1]
	v_mul_f32_e32 v52, v27, v223
	v_mul_f32_e32 v54, v26, v223
	v_pk_mul_f32 v[40:41], v[28:29], v[216:217]
	v_pk_mul_f32 v[48:49], v[24:25], v[220:221]
	v_pk_fma_f32 v[28:29], v[28:29], v[216:217], v[42:43] op_sel_hi:[1,0,1]
	v_pk_fma_f32 v[32:33], v[30:31], v[218:219], v[44:45] op_sel_hi:[1,1,0] neg_lo:[0,0,1] neg_hi:[0,0,1]
	v_pk_fma_f32 v[34:35], v[30:31], v[218:219], v[46:47] op_sel:[1,0,0] op_sel_hi:[0,1,0]
	v_pk_fma_f32 v[24:25], v[24:25], v[220:221], v[50:51] op_sel_hi:[1,0,1]
	v_pk_fma_f32 v[36:37], v[26:27], v[222:223], v[52:53] op_sel_hi:[1,1,0] neg_lo:[0,0,1] neg_hi:[0,0,1]
	v_pk_fma_f32 v[38:39], v[26:27], v[222:223], v[54:55] op_sel:[1,0,0] op_sel_hi:[0,1,0]
	v_sub_f32_e32 v28, v40, v42
	v_sub_f32_e32 v24, v48, v50
	v_mov_b32_e32 v30, v32
	v_mov_b32_e32 v31, v34
	v_mov_b32_e32 v26, v36
	v_mov_b32_e32 v27, v38
.LBB0_625:
	s_or_b64 exec, exec, s[24:25]
	v_cvt_pk_bf16_f32 v28, v28, v29
	v_cvt_pk_bf16_f32 v29, v30, v31
	v_cvt_pk_bf16_f32 v30, v24, v25
	v_cvt_pk_bf16_f32 v31, v26, v27
	global_store_dwordx4 v[90:91], v[28:31], off offset:256
	s_and_saveexec_b64 s[24:25], vcc
	s_cbranch_execz .LBB0_627
	v_lshl_add_u64 v[28:29], v[88:89], 0, v[66:67]
	s_nop 0
	s_waitcnt vmcnt(9)
	v_pk_mul_f32 v[34:35], v[20:21], v[224:225] op_sel:[1,1] op_sel_hi:[0,1]
	v_mul_f32_e32 v36, v23, v227
	v_mul_f32_e32 v38, v22, v227
	v_pk_mul_f32 v[42:43], v[16:17], v[228:229] op_sel:[1,1] op_sel_hi:[0,1]
	v_mul_f32_e32 v44, v19, v231
	v_mul_f32_e32 v46, v18, v231
	v_pk_mul_f32 v[32:33], v[20:21], v[224:225]
	v_pk_mul_f32 v[40:41], v[16:17], v[228:229]
	v_pk_fma_f32 v[20:21], v[20:21], v[224:225], v[34:35] op_sel_hi:[1,0,1]
	v_pk_fma_f32 v[24:25], v[22:23], v[226:227], v[36:37] op_sel_hi:[1,1,0] neg_lo:[0,0,1] neg_hi:[0,0,1]
	v_pk_fma_f32 v[26:27], v[22:23], v[226:227], v[38:39] op_sel:[1,0,0] op_sel_hi:[0,1,0]
	v_pk_fma_f32 v[16:17], v[16:17], v[228:229], v[42:43] op_sel_hi:[1,0,1]
	v_pk_fma_f32 v[28:29], v[18:19], v[230:231], v[44:45] op_sel_hi:[1,1,0] neg_lo:[0,0,1] neg_hi:[0,0,1]
	v_pk_fma_f32 v[30:31], v[18:19], v[230:231], v[46:47] op_sel:[1,0,0] op_sel_hi:[0,1,0]
	v_sub_f32_e32 v20, v32, v34
	v_sub_f32_e32 v16, v40, v42
	v_mov_b32_e32 v22, v24
	v_mov_b32_e32 v23, v26
	v_mov_b32_e32 v18, v28
	v_mov_b32_e32 v19, v30
.LBB0_627:
	s_or_b64 exec, exec, s[24:25]
	v_cvt_pk_bf16_f32 v20, v20, v21
	v_cvt_pk_bf16_f32 v21, v22, v23
	v_cvt_pk_bf16_f32 v22, v16, v17
	v_cvt_pk_bf16_f32 v23, v18, v19
	global_store_dwordx4 v[82:83], v[20:23], off offset:256
	s_and_saveexec_b64 s[24:25], vcc
	s_cbranch_execz .LBB0_629
	v_lshl_add_u64 v[20:21], v[80:81], 0, v[66:67]
	s_nop 0
	s_waitcnt vmcnt(8)
	v_pk_mul_f32 v[26:27], v[12:13], v[232:233] op_sel:[1,1] op_sel_hi:[0,1]
	v_mul_f32_e32 v28, v15, v235
	v_mul_f32_e32 v30, v14, v235
	v_pk_mul_f32 v[34:35], v[8:9], v[236:237] op_sel:[1,1] op_sel_hi:[0,1]
	v_mul_f32_e32 v36, v11, v239
	v_mul_f32_e32 v38, v10, v239
	v_pk_mul_f32 v[24:25], v[12:13], v[232:233]
	v_pk_mul_f32 v[32:33], v[8:9], v[236:237]
	v_pk_fma_f32 v[12:13], v[12:13], v[232:233], v[26:27] op_sel_hi:[1,0,1]
	v_pk_fma_f32 v[16:17], v[14:15], v[234:235], v[28:29] op_sel_hi:[1,1,0] neg_lo:[0,0,1] neg_hi:[0,0,1]
	v_pk_fma_f32 v[18:19], v[14:15], v[234:235], v[30:31] op_sel:[1,0,0] op_sel_hi:[0,1,0]
	v_pk_fma_f32 v[8:9], v[8:9], v[236:237], v[34:35] op_sel_hi:[1,0,1]
	v_pk_fma_f32 v[20:21], v[10:11], v[238:239], v[36:37] op_sel_hi:[1,1,0] neg_lo:[0,0,1] neg_hi:[0,0,1]
	v_pk_fma_f32 v[22:23], v[10:11], v[238:239], v[38:39] op_sel:[1,0,0] op_sel_hi:[0,1,0]
	v_sub_f32_e32 v12, v24, v26
	v_sub_f32_e32 v8, v32, v34
	v_mov_b32_e32 v14, v16
	v_mov_b32_e32 v15, v18
	v_mov_b32_e32 v10, v20
	v_mov_b32_e32 v11, v22
.LBB0_629:
	s_or_b64 exec, exec, s[24:25]
	v_cvt_pk_bf16_f32 v12, v12, v13
	v_cvt_pk_bf16_f32 v13, v14, v15
	v_cvt_pk_bf16_f32 v14, v8, v9
	v_cvt_pk_bf16_f32 v15, v10, v11
	global_store_dwordx4 v[74:75], v[12:15], off offset:256
	s_and_saveexec_b64 s[24:25], vcc
	s_cbranch_execz .LBB0_631
	v_lshl_add_u64 v[12:13], v[72:73], 0, v[66:67]
	s_nop 0
	s_waitcnt vmcnt(7)
	v_pk_mul_f32 v[18:19], v[4:5], v[240:241] op_sel:[1,1] op_sel_hi:[0,1]
	v_mul_f32_e32 v20, v7, v243
	v_mul_f32_e32 v22, v6, v243
	v_pk_mul_f32 v[26:27], v[0:1], v[244:245] op_sel:[1,1] op_sel_hi:[0,1]
	v_mul_f32_e32 v28, v3, v247
	v_mul_f32_e32 v30, v2, v247
	v_pk_mul_f32 v[16:17], v[4:5], v[240:241]
	v_pk_mul_f32 v[24:25], v[0:1], v[244:245]
	v_pk_fma_f32 v[4:5], v[4:5], v[240:241], v[18:19] op_sel_hi:[1,0,1]
	v_pk_fma_f32 v[8:9], v[6:7], v[242:243], v[20:21] op_sel_hi:[1,1,0] neg_lo:[0,0,1] neg_hi:[0,0,1]
	v_pk_fma_f32 v[10:11], v[6:7], v[242:243], v[22:23] op_sel:[1,0,0] op_sel_hi:[0,1,0]
	v_pk_fma_f32 v[0:1], v[0:1], v[244:245], v[26:27] op_sel_hi:[1,0,1]
	v_pk_fma_f32 v[12:13], v[2:3], v[246:247], v[28:29] op_sel_hi:[1,1,0] neg_lo:[0,0,1] neg_hi:[0,0,1]
	v_pk_fma_f32 v[14:15], v[2:3], v[246:247], v[30:31] op_sel:[1,0,0] op_sel_hi:[0,1,0]
	v_sub_f32_e32 v4, v16, v18
	v_sub_f32_e32 v0, v24, v26
	v_mov_b32_e32 v6, v8
	v_mov_b32_e32 v7, v10
	v_mov_b32_e32 v2, v12
	v_mov_b32_e32 v3, v14

.LBB0_1005:
	s_or_b64 exec, exec, s[0:1]
	s_waitcnt lgkmcnt(0)
	s_barrier
	s_and_saveexec_b64 s[0:1], s[38:39]
	s_cbranch_execz .LBB0_932
	v_lshlrev_b64 v[0:1], 6, v[0:1]
	v_lshl_add_u64 v[0:1], s[86:87], 0, v[0:1]
	global_load_dwordx2 v[202:203], v[0:1], off sc1
	global_load_dwordx2 v[204:205], v[0:1], off offset:8 sc1
	global_load_dwordx2 v[206:207], v[0:1], off offset:16 sc1
	global_load_dwordx2 v[208:209], v[0:1], off offset:24 sc1
	global_load_dwordx2 v[210:211], v[0:1], off offset:32 sc1
	global_load_dwordx2 v[212:213], v[0:1], off offset:40 sc1
	global_load_dwordx2 v[214:215], v[0:1], off offset:48 sc1
	global_load_dwordx2 v[216:217], v[0:1], off offset:56 sc1
	s_mov_b32 s4, 0x3a000000
	s_waitcnt vmcnt(0)
	v_add_f32_e32 v5, 0, v202
	v_add_f32_e32 v6, 0, v203
	v_add_f32_e32 v5, v5, v204
	v_add_f32_e32 v6, v6, v205
	v_add_f32_e32 v5, v5, v206
	v_add_f32_e32 v6, v6, v207
	v_add_f32_e32 v5, v5, v208
	v_add_f32_e32 v6, v6, v209
	v_add_f32_e32 v5, v5, v210
	v_add_f32_e32 v6, v6, v211
	v_add_f32_e32 v5, v5, v212
	v_add_f32_e32 v6, v6, v213
	v_add_f32_e32 v2, v5, v214
	v_add_f32_e32 v3, v6, v215
	v_add_f32_e32 v0, v2, v216
	v_mul_f32_e32 v0, 0x3a000000, v0
	v_add_f32_e32 v1, v3, v217
	v_mul_f32_e32 v2, v0, v0
	v_fma_f32 v1, v1, s4, -v2
	v_max_f32_e32 v1, 0, v1
	v_add_f32_e32 v1, 0x3727c5ac, v1
	s_mov_b32 s4, 0xf800000
	v_cmp_gt_f32_e32 vcc, s4, v1
	v_mul_f32_e32 v2, 0x4f800000, v1
	s_nop 0
	v_cndmask_b32_e32 v1, v1, v2, vcc
	v_sqrt_f32_e32 v2, v1
	s_nop 0
	v_add_u32_e32 v3, -1, v2
	v_fma_f32 v5, -v3, v2, v1
	v_cmp_ge_f32_e64 s[38:39], 0, v5
	v_add_u32_e32 v5, 1, v2
	s_nop 0
	v_cndmask_b32_e64 v3, v2, v3, s[38:39]
	v_fma_f32 v2, -v5, v2, v1
	v_cmp_lt_f32_e64 s[38:39], 0, v2
	s_nop 1
	v_cndmask_b32_e64 v2, v3, v5, s[38:39]
	v_mul_f32_e32 v3, 0x37800000, v2
	v_cndmask_b32_e32 v2, v2, v3, vcc
	v_cmp_class_f32_e32 vcc, v1, v180
	s_nop 1
	v_cndmask_b32_e32 v1, v2, v1, vcc
	v_div_scale_f32 v2, s[4:5], v1, v1, 1.0
	v_rcp_f32_e32 v3, v2
	s_nop 0
	v_fma_f32 v5, -v2, v3, 1.0
	v_fmac_f32_e32 v3, v5, v3
	v_div_scale_f32 v5, vcc, 1.0, v1, 1.0
	v_mul_f32_e32 v6, v5, v3
	v_fma_f32 v7, -v2, v6, v5
	v_fmac_f32_e32 v6, v7, v3
	v_fma_f32 v2, -v2, v6, v5
	v_div_fmas_f32 v2, v2, v3, v6
	v_div_fixup_f32 v1, v2, v1, 1.0
	v_lshl_add_u32 v2, v4, 3, 0
	ds_write_b64 v2, v[0:1] offset:8192
	s_branch .LBB0_932

.LBB0_1286:
	s_or_b64 exec, exec, s[94:95]
	s_mov_b64 s[4:5], s[56:57]
	s_waitcnt lgkmcnt(0)
	s_barrier
	s_and_saveexec_b64 s[94:95], s[38:39]
	s_cbranch_execz .LBB0_1213
	v_lshlrev_b64 v[0:1], 6, v[0:1]
	v_lshl_add_u64 v[0:1], s[10:11], 0, v[0:1]
	global_load_dwordx2 v[202:203], v[0:1], off sc1
	global_load_dwordx2 v[204:205], v[0:1], off offset:8 sc1
	global_load_dwordx2 v[206:207], v[0:1], off offset:16 sc1
	global_load_dwordx2 v[208:209], v[0:1], off offset:24 sc1
	global_load_dwordx2 v[210:211], v[0:1], off offset:32 sc1
	global_load_dwordx2 v[212:213], v[0:1], off offset:40 sc1
	global_load_dwordx2 v[214:215], v[0:1], off offset:48 sc1
	global_load_dwordx2 v[216:217], v[0:1], off offset:56 sc1
	s_mov_b32 s0, 0x3a000000
	s_waitcnt vmcnt(0)
	v_add_f32_e32 v5, 0, v202
	v_add_f32_e32 v6, 0, v203
	v_add_f32_e32 v5, v5, v204
	v_add_f32_e32 v6, v6, v205
	v_add_f32_e32 v5, v5, v206
	v_add_f32_e32 v6, v6, v207
	v_add_f32_e32 v5, v5, v208
	v_add_f32_e32 v6, v6, v209
	v_add_f32_e32 v5, v5, v210
	v_add_f32_e32 v6, v6, v211
	v_add_f32_e32 v5, v5, v212
	v_add_f32_e32 v6, v6, v213
	v_add_f32_e32 v2, v5, v214
	v_add_f32_e32 v3, v6, v215
	v_add_f32_e32 v0, v2, v216
	v_mul_f32_e32 v0, 0x3a000000, v0
	v_add_f32_e32 v1, v3, v217
	v_mul_f32_e32 v2, v0, v0
	v_fma_f32 v1, v1, s0, -v2
	v_max_f32_e32 v1, 0, v1
	v_add_f32_e32 v1, 0x3727c5ac, v1
	s_mov_b32 s0, 0xf800000
	v_cmp_gt_f32_e32 vcc, s0, v1
	v_mul_f32_e32 v2, 0x4f800000, v1
	s_nop 0
	v_cndmask_b32_e32 v1, v1, v2, vcc
	v_sqrt_f32_e32 v2, v1
	s_nop 0
	v_add_u32_e32 v3, -1, v2
	v_fma_f32 v5, -v3, v2, v1
	v_cmp_ge_f32_e64 s[38:39], 0, v5
	v_add_u32_e32 v5, 1, v2
	s_nop 0
	v_cndmask_b32_e64 v3, v2, v3, s[38:39]
	v_fma_f32 v2, -v5, v2, v1
	v_cmp_lt_f32_e64 s[38:39], 0, v2
	s_nop 1
	v_cndmask_b32_e64 v2, v3, v5, s[38:39]
	v_mul_f32_e32 v3, 0x37800000, v2
	v_cndmask_b32_e32 v2, v2, v3, vcc
	v_cmp_class_f32_e32 vcc, v1, v196
	s_nop 1
	v_cndmask_b32_e32 v1, v2, v1, vcc
	v_div_scale_f32 v2, s[0:1], v1, v1, 1.0
	v_rcp_f32_e32 v3, v2
	s_nop 0
	v_fma_f32 v5, -v2, v3, 1.0
	v_fmac_f32_e32 v3, v5, v3
	v_div_scale_f32 v5, vcc, 1.0, v1, 1.0
	v_mul_f32_e32 v6, v5, v3
	v_fma_f32 v7, -v2, v6, v5
	v_fmac_f32_e32 v6, v7, v3
	v_fma_f32 v2, -v2, v6, v5
	v_div_fmas_f32 v2, v2, v3, v6
	v_div_fixup_f32 v1, v2, v1, 1.0
	v_lshl_add_u32 v2, v4, 3, 0
	ds_write_b64 v2, v[0:1] offset:8192
	s_branch .LBB0_1213

.LBB0_1799:
	s_or_b64 exec, exec, s[4:5]
	s_waitcnt lgkmcnt(0)
	s_barrier
	s_and_saveexec_b64 s[4:5], s[36:37]
	s_cbranch_execz .LBB0_1726
	v_lshlrev_b64 v[0:1], 6, v[0:1]
	v_lshl_add_u64 v[0:1], s[52:53], 0, v[0:1]
	global_load_dwordx2 v[202:203], v[0:1], off sc1
	global_load_dwordx2 v[204:205], v[0:1], off offset:8 sc1
	global_load_dwordx2 v[206:207], v[0:1], off offset:16 sc1
	global_load_dwordx2 v[208:209], v[0:1], off offset:24 sc1
	global_load_dwordx2 v[210:211], v[0:1], off offset:32 sc1
	global_load_dwordx2 v[212:213], v[0:1], off offset:40 sc1
	global_load_dwordx2 v[214:215], v[0:1], off offset:48 sc1
	global_load_dwordx2 v[216:217], v[0:1], off offset:56 sc1
	s_mov_b32 s6, 0x3a000000
	s_waitcnt vmcnt(0)
	v_add_f32_e32 v5, 0, v202
	v_add_f32_e32 v6, 0, v203
	v_add_f32_e32 v5, v5, v204
	v_add_f32_e32 v6, v6, v205
	v_add_f32_e32 v5, v5, v206
	v_add_f32_e32 v6, v6, v207
	v_add_f32_e32 v5, v5, v208
	v_add_f32_e32 v6, v6, v209
	v_add_f32_e32 v5, v5, v210
	v_add_f32_e32 v6, v6, v211
	v_add_f32_e32 v5, v5, v212
	v_add_f32_e32 v6, v6, v213
	v_add_f32_e32 v2, v5, v214
	v_add_f32_e32 v3, v6, v215
	v_add_f32_e32 v0, v2, v216
	v_mul_f32_e32 v0, 0x3a000000, v0
	v_add_f32_e32 v1, v3, v217
	v_mul_f32_e32 v2, v0, v0
	v_fma_f32 v1, v1, s6, -v2
	v_max_f32_e32 v1, 0, v1
	v_add_f32_e32 v1, 0x3727c5ac, v1
	s_mov_b32 s6, 0xf800000
	v_cmp_gt_f32_e32 vcc, s6, v1
	v_mul_f32_e32 v2, 0x4f800000, v1
	s_nop 0
	v_cndmask_b32_e32 v1, v1, v2, vcc
	v_sqrt_f32_e32 v2, v1
	s_nop 0
	v_add_u32_e32 v3, -1, v2
	v_fma_f32 v5, -v3, v2, v1
	v_cmp_ge_f32_e64 s[36:37], 0, v5
	v_add_u32_e32 v5, 1, v2
	s_nop 0
	v_cndmask_b32_e64 v3, v2, v3, s[36:37]
	v_fma_f32 v2, -v5, v2, v1
	v_cmp_lt_f32_e64 s[36:37], 0, v2
	s_nop 1
	v_cndmask_b32_e64 v2, v3, v5, s[36:37]
	v_mul_f32_e32 v3, 0x37800000, v2
	v_cndmask_b32_e32 v2, v2, v3, vcc
	v_cmp_class_f32_e32 vcc, v1, v196
	s_nop 1
	v_cndmask_b32_e32 v1, v2, v1, vcc
	v_div_scale_f32 v2, s[6:7], v1, v1, 1.0
	v_rcp_f32_e32 v3, v2
	s_nop 0
	v_fma_f32 v5, -v2, v3, 1.0
	v_fmac_f32_e32 v3, v5, v3
	v_div_scale_f32 v5, vcc, 1.0, v1, 1.0
	v_mul_f32_e32 v6, v5, v3
	v_fma_f32 v7, -v2, v6, v5
	v_fmac_f32_e32 v6, v7, v3
	v_fma_f32 v2, -v2, v6, v5
	v_div_fmas_f32 v2, v2, v3, v6
	v_div_fixup_f32 v1, v2, v1, 1.0
	v_lshl_add_u32 v2, v4, 3, 0
	ds_write_b64 v2, v[0:1] offset:8192
	s_branch .LBB0_1726

.LBB0_2132:
	s_or_b64 exec, exec, s[92:93]
	s_waitcnt lgkmcnt(0)
	s_barrier
	s_and_saveexec_b64 s[92:93], s[36:37]
	s_cbranch_execz .LBB0_2059
	v_lshlrev_b64 v[0:1], 6, v[0:1]
	v_lshl_add_u64 v[0:1], s[50:51], 0, v[0:1]
	global_load_dwordx2 v[202:203], v[0:1], off sc1
	global_load_dwordx2 v[204:205], v[0:1], off offset:8 sc1
	global_load_dwordx2 v[206:207], v[0:1], off offset:16 sc1
	global_load_dwordx2 v[208:209], v[0:1], off offset:24 sc1
	global_load_dwordx2 v[210:211], v[0:1], off offset:32 sc1
	global_load_dwordx2 v[212:213], v[0:1], off offset:40 sc1
	global_load_dwordx2 v[214:215], v[0:1], off offset:48 sc1
	global_load_dwordx2 v[216:217], v[0:1], off offset:56 sc1
	s_mov_b32 s0, 0x3a000000
	s_waitcnt vmcnt(0)
	v_add_f32_e32 v5, 0, v202
	v_add_f32_e32 v6, 0, v203
	v_add_f32_e32 v5, v5, v204
	v_add_f32_e32 v6, v6, v205
	v_add_f32_e32 v5, v5, v206
	v_add_f32_e32 v6, v6, v207
	v_add_f32_e32 v5, v5, v208
	v_add_f32_e32 v6, v6, v209
	v_add_f32_e32 v5, v5, v210
	v_add_f32_e32 v6, v6, v211
	v_add_f32_e32 v5, v5, v212
	v_add_f32_e32 v6, v6, v213
	v_add_f32_e32 v2, v5, v214
	v_add_f32_e32 v3, v6, v215
	v_add_f32_e32 v0, v2, v216
	v_mul_f32_e32 v0, 0x3a000000, v0
	v_add_f32_e32 v1, v3, v217
	v_mul_f32_e32 v2, v0, v0
	v_fma_f32 v1, v1, s0, -v2
	v_max_f32_e32 v1, 0, v1
	v_add_f32_e32 v1, 0x3727c5ac, v1
	s_mov_b32 s0, 0xf800000
	v_cmp_gt_f32_e32 vcc, s0, v1
	v_mul_f32_e32 v2, 0x4f800000, v1
	s_nop 0
	v_cndmask_b32_e32 v1, v1, v2, vcc
	v_sqrt_f32_e32 v2, v1
	s_nop 0
	v_add_u32_e32 v3, -1, v2
	v_fma_f32 v5, -v3, v2, v1
	v_cmp_ge_f32_e64 s[36:37], 0, v5
	v_add_u32_e32 v5, 1, v2
	s_nop 0
	v_cndmask_b32_e64 v3, v2, v3, s[36:37]
	v_fma_f32 v2, -v5, v2, v1
	v_cmp_lt_f32_e64 s[36:37], 0, v2
	s_nop 1
	v_cndmask_b32_e64 v2, v3, v5, s[36:37]
	v_mul_f32_e32 v3, 0x37800000, v2
	v_cndmask_b32_e32 v2, v2, v3, vcc
	v_cmp_class_f32_e32 vcc, v1, v182
	s_nop 1
	v_cndmask_b32_e32 v1, v2, v1, vcc
	v_div_scale_f32 v2, s[0:1], v1, v1, 1.0
	v_rcp_f32_e32 v3, v2
	s_nop 0
	v_fma_f32 v5, -v2, v3, 1.0
	v_fmac_f32_e32 v3, v5, v3
	v_div_scale_f32 v5, vcc, 1.0, v1, 1.0
	v_mul_f32_e32 v6, v5, v3
	v_fma_f32 v7, -v2, v6, v5
	v_fmac_f32_e32 v6, v7, v3
	v_fma_f32 v2, -v2, v6, v5
	v_div_fmas_f32 v2, v2, v3, v6
	v_div_fixup_f32 v1, v2, v1, 1.0
	v_lshl_add_u32 v2, v4, 3, 0
	ds_write_b64 v2, v[0:1] offset:8192
	s_branch .LBB0_2059

	.amdhsa_kernel _Z8mega_fwd4Args
		.amdhsa_group_segment_fixed_size 0
		.amdhsa_private_segment_fixed_size 0
		.amdhsa_kernarg_size 424
		.amdhsa_user_sgpr_count 2
		.amdhsa_user_sgpr_dispatch_ptr 0
		.amdhsa_user_sgpr_queue_ptr 0
		.amdhsa_user_sgpr_kernarg_segment_ptr 1
		.amdhsa_user_sgpr_dispatch_id 0
		.amdhsa_user_sgpr_kernarg_preload_length 0
		.amdhsa_user_sgpr_kernarg_preload_offset 0
		.amdhsa_user_sgpr_private_segment_size 0
		.amdhsa_uses_dynamic_stack 0
		.amdhsa_enable_private_segment 0
		.amdhsa_system_sgpr_workgroup_id_x 1
		.amdhsa_system_sgpr_workgroup_id_y 0
		.amdhsa_system_sgpr_workgroup_id_z 0
		.amdhsa_system_sgpr_workgroup_info 0
		.amdhsa_system_vgpr_workitem_id 2
		.amdhsa_next_free_vgpr 256
		.amdhsa_next_free_sgpr 102
		.amdhsa_accum_offset 256
		.amdhsa_reserve_vcc 1
		.amdhsa_float_round_mode_32 0
		.amdhsa_float_round_mode_16_64 0
		.amdhsa_float_denorm_mode_32 3
		.amdhsa_float_denorm_mode_16_64 3
		.amdhsa_dx10_clamp 1
		.amdhsa_ieee_mode 1
		.amdhsa_fp16_overflow 0
		.amdhsa_tg_split 0
		.amdhsa_exception_fp_ieee_invalid_op 0
		.amdhsa_exception_fp_denorm_src 0
		.amdhsa_exception_fp_ieee_div_zero 0
		.amdhsa_exception_fp_ieee_overflow 0
		.amdhsa_exception_fp_ieee_underflow 0
		.amdhsa_exception_fp_ieee_inexact 0
		.amdhsa_exception_int_div_zero 0
	.end_amdhsa_kernel

amdhsa.kernels:
  - .agpr_count:     0
    .args:
      - .offset:         0
        .size:           168
        .value_kind:     by_value
      - .offset:         168
        .size:           4
        .value_kind:     hidden_block_count_x
      - .offset:         172
        .size:           4
        .value_kind:     hidden_block_count_y
      - .offset:         176
        .size:           4
        .value_kind:     hidden_block_count_z
      - .offset:         180
        .size:           2
        .value_kind:     hidden_group_size_x
      - .offset:         182
        .size:           2
        .value_kind:     hidden_group_size_y
      - .offset:         184
        .size:           2
        .value_kind:     hidden_group_size_z
      - .offset:         186
        .size:           2
        .value_kind:     hidden_remainder_x
      - .offset:         188
        .size:           2
        .value_kind:     hidden_remainder_y
      - .offset:         190
        .size:           2
        .value_kind:     hidden_remainder_z
      - .offset:         208
        .size:           8
        .value_kind:     hidden_global_offset_x
      - .offset:         216
        .size:           8
        .value_kind:     hidden_global_offset_y
      - .offset:         224
        .size:           8
        .value_kind:     hidden_global_offset_z
      - .offset:         232
        .size:           2
        .value_kind:     hidden_grid_dims
      - .offset:         256
        .size:           8
        .value_kind:     hidden_multigrid_sync_arg
      - .offset:         288
        .size:           4
        .value_kind:     hidden_dynamic_lds_size
    .group_segment_fixed_size: 0
    .kernarg_segment_align: 8
    .kernarg_segment_size: 424
    .language:       OpenCL C
    .language_version:
      - 2
      - 0
    .max_flat_workgroup_size: 512
    .name:           _Z8mega_fwd4Args
    .private_segment_fixed_size: 0
    .sgpr_count:     108
    .sgpr_spill_count: 175
    .symbol:         _Z8mega_fwd4Args.kd
    .uniform_work_group_size: 1
    .uses_dynamic_stack: false
    .vgpr_count:     256
    .vgpr_spill_count: 0
    .wavefront_size: 64
